# grid barrier: each workgroup issues its L1 invalidate (buffer_inv sc1) at arrival, right after its arrival atomic, instead of after the release; its completion is still waited before the workgroup lea
# speedup vs baseline: 1.0103x; 1.0103x over previous
.LBB0_79:
	v_readlane_b32 s10, v253, 3
	s_lshl_b32 s10, s10, 8
	v_readlane_b32 s12, v253, 1
	v_readlane_b32 s13, v253, 2
	s_add_u32 s10, s12, s10
	s_addc_u32 s11, s13, 0
	v_mov_b32_e32 v1, 0x1000
	v_mov_b32_e32 v3, 1
	global_atomic_add v3, v1, v3, s[10:11] offset:1024 sc0
	buffer_inv sc1
	v_cvt_f32_u32_e32 v1, v2
	v_sub_u32_e32 v4, 0, v2
	v_rcp_iflag_f32_e32 v1, v1
	s_nop 0
	v_mul_f32_e32 v1, 0x4f7ffffe, v1
	v_cvt_u32_f32_e32 v1, v1
	v_mul_lo_u32 v4, v4, v1
	v_mul_hi_u32 v4, v1, v4
	v_add_u32_e32 v1, v1, v4
	s_waitcnt vmcnt(1)
	v_mul_hi_u32 v1, v3, v1
	v_mul_lo_u32 v4, v1, v2
	v_sub_u32_e32 v4, v3, v4
	v_add_u32_e32 v5, 1, v1
	v_cmp_ge_u32_e32 vcc, v4, v2
	v_add_u32_e32 v3, 1, v3
	s_nop 0
	v_cndmask_b32_e32 v1, v1, v5, vcc
	v_sub_u32_e32 v5, v4, v2
	v_cndmask_b32_e32 v4, v4, v5, vcc
	v_add_u32_e32 v5, 1, v1
	v_cmp_ge_u32_e32 vcc, v4, v2
	s_nop 1
	v_cndmask_b32_e32 v1, v1, v5, vcc
	v_mul_lo_u32 v4, v2, v1
	v_add_u32_e32 v2, v4, v2
	v_cmp_ne_u32_e32 vcc, v3, v2
	s_waitcnt lgkmcnt(0)
	v_add_u32_e32 v4, 1, v1
	v_mul_lo_u32 v4, v4, v0
	v_mov_b32_e32 v2, 0x63000
	s_cbranch_vccnz .Lxb0_wait
	buffer_wbl2 sc1
	s_waitcnt vmcnt(0)
	v_mov_b32_e32 v3, 1
	global_atomic_add v2, v3, s[76:77] offset:1024

.Lxb0_done:
	s_waitcnt vmcnt(0)
.LBB0_111:
	s_or_b64 exec, exec, s[8:9]
	s_waitcnt lgkmcnt(0)
	s_barrier

.LBB0_139:
	v_readlane_b32 s6, v253, 3
	s_lshl_b32 s6, s6, 8
	v_readlane_b32 s8, v253, 1
	v_readlane_b32 s9, v253, 2
	s_add_u32 s6, s8, s6
	s_addc_u32 s7, s9, 0
	v_mov_b32_e32 v1, 0x1000
	v_mov_b32_e32 v3, 1
	global_atomic_add v3, v1, v3, s[6:7] offset:1024 sc0
	buffer_inv sc1
	v_cvt_f32_u32_e32 v1, v2
	v_sub_u32_e32 v4, 0, v2
	v_rcp_iflag_f32_e32 v1, v1
	s_nop 0
	v_mul_f32_e32 v1, 0x4f7ffffe, v1
	v_cvt_u32_f32_e32 v1, v1
	v_mul_lo_u32 v4, v4, v1
	v_mul_hi_u32 v4, v1, v4
	v_add_u32_e32 v1, v1, v4
	s_waitcnt vmcnt(1)
	v_mul_hi_u32 v1, v3, v1
	v_mul_lo_u32 v4, v1, v2
	v_sub_u32_e32 v4, v3, v4
	v_add_u32_e32 v5, 1, v1
	v_cmp_ge_u32_e32 vcc, v4, v2
	v_add_u32_e32 v3, 1, v3
	s_nop 0
	v_cndmask_b32_e32 v1, v1, v5, vcc
	v_sub_u32_e32 v5, v4, v2
	v_cndmask_b32_e32 v4, v4, v5, vcc
	v_add_u32_e32 v5, 1, v1
	v_cmp_ge_u32_e32 vcc, v4, v2
	s_nop 1
	v_cndmask_b32_e32 v1, v1, v5, vcc
	v_mul_lo_u32 v4, v2, v1
	v_add_u32_e32 v2, v4, v2
	v_cmp_ne_u32_e32 vcc, v3, v2
	s_waitcnt lgkmcnt(0)
	v_add_u32_e32 v4, 1, v1
	v_mul_lo_u32 v4, v4, v0
	v_mov_b32_e32 v2, 0x63000
	s_cbranch_vccnz .Lxb1_wait
	buffer_wbl2 sc1
	s_waitcnt vmcnt(0)
	v_mov_b32_e32 v3, 1
	global_atomic_add v2, v3, s[76:77] offset:1024

.Lxb1_done:
	s_waitcnt vmcnt(0)
.LBB0_171:
	s_or_b64 exec, exec, s[2:3]
	s_waitcnt lgkmcnt(0)
	s_barrier

.LBB0_180:
	s_add_i32 s85, s85, 1
	s_cmp_lt_i32 s85, s43
	s_cselect_b64 s[8:9], -1, 0
	s_cmp_eq_u32 s85, s43
	s_cselect_b64 s[26:27], -1, 0
	s_min_i32 s35, s85, s43
	s_mov_b32 s34, s70
	s_waitcnt lgkmcnt(0)
	s_mul_i32 s35, s35, s92
	v_readlane_b32 s70, v253, 44
	s_add_i32 s35, s35, s70
	s_min_i32 s35, s35, 0x40f
	s_ashr_i32 s70, s35, 31
	s_lshr_b32 s70, s70, 29
	s_add_i32 s70, s35, s70
	s_mov_b64 s[4:5], s[74:75]
	s_ashr_i32 s74, s70, 3
	s_and_b32 s70, s70, -8
	s_and_b64 s[26:27], s[26:27], s[68:69]
	s_sub_i32 s35, s35, s70
	s_cmp_lt_i32 s35, 0
	s_cselect_b32 s70, s45, 0x82
	s_mul_i32 s35, s35, s70
	s_add_i32 s35, s35, s74
	s_mul_hi_i32 s70, s35, 0xd20d20d3
	s_add_i32 s70, s70, s35
	s_lshr_b32 s74, s70, 31
	s_ashr_i32 s70, s70, 6
	s_add_i32 s70, s70, s74
	s_mov_b64 s[6:7], s[76:77]
	s_mul_i32 s76, s70, 3
	s_sub_i32 s74, 40, s76
	s_min_u32 s77, s74, 3
	s_mulk_i32 s70, 0x4e
	s_sub_i32 s86, s35, s70
	v_cvt_f32_ubyte0_e32 v1, s77
	v_cvt_f32_i32_e32 v0, s86
	v_rcp_iflag_f32_e32 v2, v1
	s_mov_b32 s35, s46
	s_ashr_i32 s46, s86, 30
	s_or_b32 s46, s46, 1
	v_mul_f32_e32 v2, v0, v2
	v_trunc_f32_e32 v2, v2
	v_fma_f32 v0, -v2, v1, v0
	v_cvt_i32_f32_e32 v2, v2
	v_cmp_ge_f32_e64 s[74:75], |v0|, v1
	s_and_b64 s[74:75], s[74:75], exec
	s_cselect_b32 s46, s46, 0
	v_readfirstlane_b32 s70, v2
	s_add_i32 s70, s70, s46
	s_mul_i32 s46, s70, s77
	s_sub_i32 s46, s86, s46
	s_sext_i32_i8 s46, s46
	s_add_i32 s46, s76, s46
	s_or_b64 s[92:93], s[8:9], s[26:27]
	s_lshl_b32 s8, s46, 8
	s_ashr_i32 s9, s8, 31
	s_lshl_b64 s[8:9], s[8:9], 12
	s_add_u32 s74, s36, s8
	s_addc_u32 s75, s37, s9
	s_and_b64 s[8:9], s[92:93], exec
	s_cselect_b32 s26, s75, s5
	s_cselect_b32 s27, s74, s4
	s_bfe_i64 s[8:9], s[70:71], 0x80000
	s_lshl_b64 s[8:9], s[8:9], 20
	s_add_u32 s76, s38, s8
	s_addc_u32 s77, s39, s9
	s_and_b64 s[8:9], s[92:93], exec
	s_cselect_b32 s86, s77, s7
	s_cselect_b32 s91, s76, s6
	s_add_u32 s4, s4, 0x80080
	s_addc_u32 s5, s5, 0
	s_add_u32 s94, s6, 0x100
	v_mov_b32_e32 v0, 0
	s_addc_u32 s95, s7, 0
	s_mov_b32 s96, -2
	v_mov_b32_e32 v1, v0
	v_mov_b32_e32 v2, v0
	v_mov_b32_e32 v3, v0
	v_mov_b32_e32 v4, v0
	v_mov_b32_e32 v5, v0
	v_mov_b32_e32 v6, v0
	v_mov_b32_e32 v7, v0
	v_mov_b32_e32 v16, v0
	v_mov_b32_e32 v17, v0
	v_mov_b32_e32 v18, v0
	v_mov_b32_e32 v19, v0
	v_mov_b32_e32 v20, v0
	v_mov_b32_e32 v21, v0
	v_mov_b32_e32 v22, v0
	v_mov_b32_e32 v23, v0
	v_mov_b32_e32 v32, v0
	v_mov_b32_e32 v33, v0
	v_mov_b32_e32 v34, v0
	v_mov_b32_e32 v35, v0
	v_mov_b32_e32 v36, v0
	v_mov_b32_e32 v37, v0
	v_mov_b32_e32 v38, v0
	v_mov_b32_e32 v39, v0
	v_mov_b32_e32 v48, v0
	v_mov_b32_e32 v49, v0
	v_mov_b32_e32 v50, v0
	v_mov_b32_e32 v51, v0
	v_mov_b32_e32 v52, v0
	v_mov_b32_e32 v53, v0
	v_mov_b32_e32 v54, v0
	v_mov_b32_e32 v55, v0
	v_mov_b32_e32 v8, v0
	v_mov_b32_e32 v9, v0
	v_mov_b32_e32 v10, v0
	v_mov_b32_e32 v11, v0
	v_mov_b32_e32 v12, v0
	v_mov_b32_e32 v13, v0
	v_mov_b32_e32 v14, v0
	v_mov_b32_e32 v15, v0
	v_mov_b32_e32 v24, v0
	v_mov_b32_e32 v25, v0
	v_mov_b32_e32 v26, v0
	v_mov_b32_e32 v27, v0
	v_mov_b32_e32 v28, v0
	v_mov_b32_e32 v29, v0
	v_mov_b32_e32 v30, v0
	v_mov_b32_e32 v31, v0
	v_mov_b32_e32 v40, v0
	v_mov_b32_e32 v41, v0
	v_mov_b32_e32 v42, v0
	v_mov_b32_e32 v43, v0
	v_mov_b32_e32 v44, v0
	v_mov_b32_e32 v45, v0
	v_mov_b32_e32 v46, v0
	v_mov_b32_e32 v47, v0
	v_mov_b32_e32 v56, v0
	v_mov_b32_e32 v57, v0
	v_mov_b32_e32 v58, v0
	v_mov_b32_e32 v59, v0
	v_mov_b32_e32 v60, v0
	v_mov_b32_e32 v61, v0
	v_mov_b32_e32 v62, v0
	v_mov_b32_e32 v63, v0
	v_mov_b32_e32 v64, v0
	v_mov_b32_e32 v65, v0
	v_mov_b32_e32 v66, v0
	v_mov_b32_e32 v67, v0
	v_mov_b32_e32 v68, v0
	v_mov_b32_e32 v69, v0
	v_mov_b32_e32 v70, v0
	v_mov_b32_e32 v71, v0
	v_mov_b32_e32 v80, v0
	v_mov_b32_e32 v81, v0
	v_mov_b32_e32 v82, v0
	v_mov_b32_e32 v83, v0
	v_mov_b32_e32 v84, v0
	v_mov_b32_e32 v85, v0
	v_mov_b32_e32 v86, v0
	v_mov_b32_e32 v87, v0
	v_mov_b32_e32 v96, v0
	v_mov_b32_e32 v97, v0
	v_mov_b32_e32 v98, v0
	v_mov_b32_e32 v99, v0
	v_mov_b32_e32 v100, v0
	v_mov_b32_e32 v101, v0
	v_mov_b32_e32 v102, v0
	v_mov_b32_e32 v103, v0
	v_mov_b32_e32 v112, v0
	v_mov_b32_e32 v113, v0
	v_mov_b32_e32 v114, v0
	v_mov_b32_e32 v115, v0
	v_mov_b32_e32 v116, v0
	v_mov_b32_e32 v117, v0
	v_mov_b32_e32 v118, v0
	v_mov_b32_e32 v119, v0
	v_mov_b32_e32 v72, v0
	v_mov_b32_e32 v73, v0
	v_mov_b32_e32 v74, v0
	v_mov_b32_e32 v75, v0
	v_mov_b32_e32 v76, v0
	v_mov_b32_e32 v77, v0
	v_mov_b32_e32 v78, v0
	v_mov_b32_e32 v79, v0
	v_mov_b32_e32 v88, v0
	v_mov_b32_e32 v89, v0
	v_mov_b32_e32 v90, v0
	v_mov_b32_e32 v91, v0
	v_mov_b32_e32 v92, v0
	v_mov_b32_e32 v93, v0
	v_mov_b32_e32 v94, v0
	v_mov_b32_e32 v95, v0
	v_mov_b32_e32 v104, v0
	v_mov_b32_e32 v105, v0
	v_mov_b32_e32 v106, v0
	v_mov_b32_e32 v107, v0
	v_mov_b32_e32 v108, v0
	v_mov_b32_e32 v109, v0
	v_mov_b32_e32 v110, v0
	v_mov_b32_e32 v111, v0
	v_mov_b32_e32 v120, v0
	v_mov_b32_e32 v121, v0
	v_mov_b32_e32 v122, v0
	v_mov_b32_e32 v123, v0
	v_mov_b32_e32 v124, v0
	v_mov_b32_e32 v125, v0
	v_mov_b32_e32 v126, v0
	v_mov_b32_e32 v127, v0
	s_nop 0
	s_nop 0
	s_nop 0
	s_nop 0
	s_nop 0
	s_nop 0
	s_nop 0
	s_nop 0
	s_nop 0

.Lxb2_done:
	s_waitcnt vmcnt(0)
.LBB0_787:
	s_or_b64 exec, exec, s[4:5]
	s_waitcnt lgkmcnt(0)
	s_barrier

.LBB0_796:
	s_add_i32 m0, s5, 0x18000
	v_lshl_add_u64 v[0:1], v[0:1], 0, s[2:3]
	s_and_b32 s41, s24, 3
	s_lshl_b32 s43, s23, 6
	s_lshl_b32 s23, s23, 13
	s_waitcnt vmcnt(2)
	s_barrier
	global_load_lds_dwordx4 v[0:1], off
	v_lshl_add_u64 v[0:1], v[2:3], 0, s[2:3]
	s_add_i32 m0, s5, 0x1a000
	s_add_i32 s44, s5, 0x8000
	s_add_i32 s45, s5, 0xa000
	global_load_lds_dwordx4 v[0:1], off
	v_lshl_add_u64 v[0:1], v[6:7], 0, s[2:3]
	s_mov_b32 m0, s44
	s_add_u32 s24, s6, 0x80080
	global_load_lds_dwordx4 v[0:1], off
	v_lshl_add_u64 v[0:1], v[4:5], 0, s[2:3]
	s_mov_b32 m0, s45
	s_addc_u32 s25, s7, 0
	global_load_lds_dwordx4 v[0:1], off
	s_add_i32 m0, s5, 0x1c000
	v_lshl_add_u64 v[0:1], s[24:25], 0, v[128:129]
	global_load_lds_dwordx4 v[0:1], off
	v_lshl_add_u64 v[0:1], s[24:25], 0, v[130:131]
	s_add_i32 m0, s5, 0x1e000
	v_bitop3_b32 v8, v144, s23, v145 bitop3:0xde
	global_load_lds_dwordx4 v[0:1], off
	s_waitcnt vmcnt(6)
	v_lshl_or_b32 v9, s41, 12, v143
	v_mov_b32_e32 v0, 0
	s_add_i32 s49, s30, s22
	s_add_i32 s51, s31, s22
	s_add_i32 s57, s34, s22
	s_add_i32 s59, s35, s22
	v_lshl_add_u64 v[138:139], v[134:135], 0, s[20:21]
	v_lshl_add_u64 v[140:141], v[136:137], 0, s[20:21]
	s_mov_b32 s46, -2
	s_mov_b64 s[20:21], 0x7680080
	v_add_u32_e32 v146, s30, v9
	v_add_u32_e32 v147, s31, v9
	v_add_u32_e32 v148, 0, v8
	s_add_i32 s47, s5, 0xc000
	s_add_i32 s48, s5, 0xe000
	s_add_i32 s50, s49, 0x2000
	s_add_i32 s56, s51, 0x2000
	v_add_u32_e32 v149, s34, v9
	v_add_u32_e32 v150, s35, v9
	s_add_i32 s58, s57, 0x2000
	s_add_i32 s84, s59, 0x2000
	v_mov_b32_e32 v1, v0
	v_mov_b32_e32 v2, v0
	v_mov_b32_e32 v3, v0
	v_mov_b32_e32 v4, v0
	v_mov_b32_e32 v5, v0
	v_mov_b32_e32 v6, v0
	v_mov_b32_e32 v7, v0
	v_mov_b32_e32 v16, v0
	v_mov_b32_e32 v17, v0
	v_mov_b32_e32 v18, v0
	v_mov_b32_e32 v19, v0
	v_mov_b32_e32 v20, v0
	v_mov_b32_e32 v21, v0
	v_mov_b32_e32 v22, v0
	v_mov_b32_e32 v23, v0
	v_mov_b32_e32 v32, v0
	v_mov_b32_e32 v33, v0
	v_mov_b32_e32 v34, v0
	v_mov_b32_e32 v35, v0
	v_mov_b32_e32 v36, v0
	v_mov_b32_e32 v37, v0
	v_mov_b32_e32 v38, v0
	v_mov_b32_e32 v39, v0
	v_mov_b32_e32 v48, v0
	v_mov_b32_e32 v49, v0
	v_mov_b32_e32 v50, v0
	v_mov_b32_e32 v51, v0
	v_mov_b32_e32 v52, v0
	v_mov_b32_e32 v53, v0
	v_mov_b32_e32 v54, v0
	v_mov_b32_e32 v55, v0
	v_mov_b32_e32 v8, v0
	v_mov_b32_e32 v9, v0
	v_mov_b32_e32 v10, v0
	v_mov_b32_e32 v11, v0
	v_mov_b32_e32 v12, v0
	v_mov_b32_e32 v13, v0
	v_mov_b32_e32 v14, v0
	v_mov_b32_e32 v15, v0
	v_mov_b32_e32 v24, v0
	v_mov_b32_e32 v25, v0
	v_mov_b32_e32 v26, v0
	v_mov_b32_e32 v27, v0
	v_mov_b32_e32 v28, v0
	v_mov_b32_e32 v29, v0
	v_mov_b32_e32 v30, v0
	v_mov_b32_e32 v31, v0
	v_mov_b32_e32 v40, v0
	v_mov_b32_e32 v41, v0
	v_mov_b32_e32 v42, v0
	v_mov_b32_e32 v43, v0
	v_mov_b32_e32 v44, v0
	v_mov_b32_e32 v45, v0
	v_mov_b32_e32 v46, v0
	v_mov_b32_e32 v47, v0
	v_mov_b32_e32 v56, v0
	v_mov_b32_e32 v57, v0
	v_mov_b32_e32 v58, v0
	v_mov_b32_e32 v59, v0
	v_mov_b32_e32 v60, v0
	v_mov_b32_e32 v61, v0
	v_mov_b32_e32 v62, v0
	v_mov_b32_e32 v63, v0
	v_mov_b32_e32 v64, v0
	v_mov_b32_e32 v65, v0
	v_mov_b32_e32 v66, v0
	v_mov_b32_e32 v67, v0
	v_mov_b32_e32 v68, v0
	v_mov_b32_e32 v69, v0
	v_mov_b32_e32 v70, v0
	v_mov_b32_e32 v71, v0
	v_mov_b32_e32 v80, v0
	v_mov_b32_e32 v81, v0
	v_mov_b32_e32 v82, v0
	v_mov_b32_e32 v83, v0
	v_mov_b32_e32 v84, v0
	v_mov_b32_e32 v85, v0
	v_mov_b32_e32 v86, v0
	v_mov_b32_e32 v87, v0
	v_mov_b32_e32 v96, v0
	v_mov_b32_e32 v97, v0
	v_mov_b32_e32 v98, v0
	v_mov_b32_e32 v99, v0
	v_mov_b32_e32 v100, v0
	v_mov_b32_e32 v101, v0
	v_mov_b32_e32 v102, v0
	v_mov_b32_e32 v103, v0
	v_mov_b32_e32 v112, v0
	v_mov_b32_e32 v113, v0
	v_mov_b32_e32 v114, v0
	v_mov_b32_e32 v115, v0
	v_mov_b32_e32 v116, v0
	v_mov_b32_e32 v117, v0
	v_mov_b32_e32 v118, v0
	v_mov_b32_e32 v119, v0
	v_mov_b32_e32 v72, v0
	v_mov_b32_e32 v73, v0
	v_mov_b32_e32 v74, v0
	v_mov_b32_e32 v75, v0
	v_mov_b32_e32 v76, v0
	v_mov_b32_e32 v77, v0
	v_mov_b32_e32 v78, v0
	v_mov_b32_e32 v79, v0
	v_mov_b32_e32 v88, v0
	v_mov_b32_e32 v89, v0
	v_mov_b32_e32 v90, v0
	v_mov_b32_e32 v91, v0
	v_mov_b32_e32 v92, v0
	v_mov_b32_e32 v93, v0
	v_mov_b32_e32 v94, v0
	v_mov_b32_e32 v95, v0
	v_mov_b32_e32 v104, v0
	v_mov_b32_e32 v105, v0
	v_mov_b32_e32 v106, v0
	v_mov_b32_e32 v107, v0
	v_mov_b32_e32 v108, v0
	v_mov_b32_e32 v109, v0
	v_mov_b32_e32 v110, v0
	v_mov_b32_e32 v111, v0
	v_mov_b32_e32 v120, v0
	v_mov_b32_e32 v121, v0
	v_mov_b32_e32 v122, v0
	v_mov_b32_e32 v123, v0
	v_mov_b32_e32 v124, v0
	v_mov_b32_e32 v125, v0
	v_mov_b32_e32 v126, v0
	v_mov_b32_e32 v127, v0
	s_barrier
	s_nop 0
	s_nop 0
	s_nop 0
	s_nop 0
	s_nop 0
	s_nop 0
	s_nop 0
	s_nop 0

.LBB0_1017:
	v_readlane_b32 s4, v253, 3
	s_lshl_b32 s4, s4, 8
	v_readlane_b32 s6, v253, 1
	v_readlane_b32 s7, v253, 2
	s_add_u32 s4, s6, s4
	s_addc_u32 s5, s7, 0
	v_mov_b32_e32 v1, 0x1000
	v_mov_b32_e32 v3, 1
	global_atomic_add v3, v1, v3, s[4:5] offset:1024 sc0
	buffer_inv sc1
	v_cvt_f32_u32_e32 v1, v2
	v_sub_u32_e32 v4, 0, v2
	v_rcp_iflag_f32_e32 v1, v1
	s_nop 0
	v_mul_f32_e32 v1, 0x4f7ffffe, v1
	v_cvt_u32_f32_e32 v1, v1
	v_mul_lo_u32 v4, v4, v1
	v_mul_hi_u32 v4, v1, v4
	v_add_u32_e32 v1, v1, v4
	s_waitcnt vmcnt(1)
	v_mul_hi_u32 v1, v3, v1
	v_mul_lo_u32 v4, v1, v2
	v_sub_u32_e32 v4, v3, v4
	v_add_u32_e32 v5, 1, v1
	v_cmp_ge_u32_e32 vcc, v4, v2
	v_add_u32_e32 v3, 1, v3
	s_nop 0
	v_cndmask_b32_e32 v1, v1, v5, vcc
	v_sub_u32_e32 v5, v4, v2
	v_cndmask_b32_e32 v4, v4, v5, vcc
	v_add_u32_e32 v5, 1, v1
	v_cmp_ge_u32_e32 vcc, v4, v2
	s_nop 1
	v_cndmask_b32_e32 v1, v1, v5, vcc
	v_mul_lo_u32 v4, v2, v1
	v_add_u32_e32 v2, v4, v2
	v_cmp_ne_u32_e32 vcc, v3, v2
	s_waitcnt lgkmcnt(0)
	v_add_u32_e32 v4, 1, v1
	v_mul_lo_u32 v4, v4, v0
	v_mov_b32_e32 v2, 0x63000
	s_cbranch_vccnz .Lxb3_wait
	buffer_wbl2 sc1
	s_waitcnt vmcnt(0)
	v_mov_b32_e32 v3, 1
	global_atomic_add v2, v3, s[76:77] offset:1024

.Lxb3_done:
	s_waitcnt vmcnt(0)
.LBB0_1049:
	s_or_b64 exec, exec, s[2:3]
	s_waitcnt lgkmcnt(0)
	s_barrier

.LBB0_1057:
	s_add_i32 s41, s41, 1
	s_cmp_lt_i32 s41, s9
	s_mov_b64 s[24:25], s[12:13]
	s_cselect_b64 s[12:13], -1, 0
	s_cmp_eq_u32 s41, s9
	s_mov_b64 s[26:27], s[16:17]
	s_mov_b32 s44, s8
	s_cselect_b64 s[16:17], -1, 0
	s_min_i32 s8, s41, s9
	s_mul_i32 s8, s8, s92
	s_add_i32 s8, s8, s96
	s_min_i32 s8, s8, 0x9f
	s_ashr_i32 s22, s8, 31
	s_lshr_b32 s22, s22, 29
	s_add_i32 s22, s8, s22
	s_ashr_i32 s23, s22, 3
	s_and_b32 s22, s22, -8
	s_and_b64 s[16:17], s[16:17], s[4:5]
	s_sub_i32 s8, s8, s22
	s_cmp_lt_i32 s8, 0
	s_cselect_b32 s22, 21, 20
	s_mul_i32 s8, s8, s22
	s_add_i32 s8, s8, s23
	s_mul_hi_i32 s22, s8, 0x2aaaaaab
	s_lshr_b32 s23, s22, 31
	s_ashr_i32 s22, s22, 1
	s_add_i32 s22, s22, s23
	s_mul_i32 s28, s22, 3
	s_sub_i32 s23, 40, s28
	s_min_u32 s29, s23, 3
	s_mul_i32 s22, s22, 12
	s_sub_i32 s46, s8, s22
	v_cvt_f32_ubyte0_e32 v1, s29
	v_cvt_f32_i32_e32 v0, s46
	v_rcp_iflag_f32_e32 v2, v1
	s_ashr_i32 s8, s46, 30
	s_or_b32 s8, s8, 1
	s_mov_b32 s45, s34
	v_mul_f32_e32 v2, v0, v2
	v_trunc_f32_e32 v2, v2
	v_fma_f32 v0, -v2, v1, v0
	v_cvt_i32_f32_e32 v2, v2
	v_cmp_ge_f32_e64 s[22:23], |v0|, v1
	s_and_b64 s[22:23], s[22:23], exec
	s_cselect_b32 s8, s8, 0
	v_readfirstlane_b32 s22, v2
	s_add_i32 s8, s22, s8
	s_mul_i32 s22, s8, s29
	s_sub_i32 s22, s46, s22
	s_sext_i32_i8 s22, s22
	s_add_i32 s34, s28, s22
	s_or_b64 s[22:23], s[12:13], s[16:17]
	s_lshl_b32 s12, s34, 8
	s_ashr_i32 s13, s12, 31
	s_lshl_b64 s[12:13], s[12:13], 11
	s_add_u32 s12, s6, s12
	s_addc_u32 s13, s7, s13
	s_and_b64 s[16:17], s[22:23], exec
	s_cselect_b32 s46, s13, s25
	s_cselect_b32 s47, s12, s24
	s_bfe_i64 s[16:17], s[8:9], 0x80000
	s_lshl_b64 s[16:17], s[16:17], 19
	s_add_u32 s16, s30, s16
	s_addc_u32 s17, s31, s17
	s_and_b64 s[28:29], s[22:23], exec
	s_cselect_b32 s48, s17, s27
	s_cselect_b32 s49, s16, s26
	s_add_u32 s24, s24, 0x40080
	s_addc_u32 s25, s25, 0
	s_add_u32 s50, s26, 0x100
	v_mov_b32_e32 v0, 0
	s_addc_u32 s51, s27, 0
	s_mov_b32 s56, -2
	v_mov_b32_e32 v1, v0
	v_mov_b32_e32 v2, v0
	v_mov_b32_e32 v3, v0
	v_mov_b32_e32 v4, v0
	v_mov_b32_e32 v5, v0
	v_mov_b32_e32 v6, v0
	v_mov_b32_e32 v7, v0
	v_mov_b32_e32 v16, v0
	v_mov_b32_e32 v17, v0
	v_mov_b32_e32 v18, v0
	v_mov_b32_e32 v19, v0
	v_mov_b32_e32 v20, v0
	v_mov_b32_e32 v21, v0
	v_mov_b32_e32 v22, v0
	v_mov_b32_e32 v23, v0
	v_mov_b32_e32 v32, v0
	v_mov_b32_e32 v33, v0
	v_mov_b32_e32 v34, v0
	v_mov_b32_e32 v35, v0
	v_mov_b32_e32 v36, v0
	v_mov_b32_e32 v37, v0
	v_mov_b32_e32 v38, v0
	v_mov_b32_e32 v39, v0
	v_mov_b32_e32 v48, v0
	v_mov_b32_e32 v49, v0
	v_mov_b32_e32 v50, v0
	v_mov_b32_e32 v51, v0
	v_mov_b32_e32 v52, v0
	v_mov_b32_e32 v53, v0
	v_mov_b32_e32 v54, v0
	v_mov_b32_e32 v55, v0
	v_mov_b32_e32 v8, v0
	v_mov_b32_e32 v9, v0
	v_mov_b32_e32 v10, v0
	v_mov_b32_e32 v11, v0
	v_mov_b32_e32 v12, v0
	v_mov_b32_e32 v13, v0
	v_mov_b32_e32 v14, v0
	v_mov_b32_e32 v15, v0
	v_mov_b32_e32 v24, v0
	v_mov_b32_e32 v25, v0
	v_mov_b32_e32 v26, v0
	v_mov_b32_e32 v27, v0
	v_mov_b32_e32 v28, v0
	v_mov_b32_e32 v29, v0
	v_mov_b32_e32 v30, v0
	v_mov_b32_e32 v31, v0
	v_mov_b32_e32 v40, v0
	v_mov_b32_e32 v41, v0
	v_mov_b32_e32 v42, v0
	v_mov_b32_e32 v43, v0
	v_mov_b32_e32 v44, v0
	v_mov_b32_e32 v45, v0
	v_mov_b32_e32 v46, v0
	v_mov_b32_e32 v47, v0
	v_mov_b32_e32 v56, v0
	v_mov_b32_e32 v57, v0
	v_mov_b32_e32 v58, v0
	v_mov_b32_e32 v59, v0
	v_mov_b32_e32 v60, v0
	v_mov_b32_e32 v61, v0
	v_mov_b32_e32 v62, v0
	v_mov_b32_e32 v63, v0
	v_mov_b32_e32 v64, v0
	v_mov_b32_e32 v65, v0
	v_mov_b32_e32 v66, v0
	v_mov_b32_e32 v67, v0
	v_mov_b32_e32 v68, v0
	v_mov_b32_e32 v69, v0
	v_mov_b32_e32 v70, v0
	v_mov_b32_e32 v71, v0
	v_mov_b32_e32 v80, v0
	v_mov_b32_e32 v81, v0
	v_mov_b32_e32 v82, v0
	v_mov_b32_e32 v83, v0
	v_mov_b32_e32 v84, v0
	v_mov_b32_e32 v85, v0
	v_mov_b32_e32 v86, v0
	v_mov_b32_e32 v87, v0
	v_mov_b32_e32 v96, v0
	s_waitcnt lgkmcnt(0)
	v_mov_b32_e32 v97, v0
	v_mov_b32_e32 v98, v0
	v_mov_b32_e32 v99, v0
	v_mov_b32_e32 v100, v0
	v_mov_b32_e32 v101, v0
	v_mov_b32_e32 v102, v0
	v_mov_b32_e32 v103, v0
	v_mov_b32_e32 v112, v0
	v_mov_b32_e32 v113, v0
	v_mov_b32_e32 v114, v0
	v_mov_b32_e32 v115, v0
	v_mov_b32_e32 v116, v0
	v_mov_b32_e32 v117, v0
	v_mov_b32_e32 v118, v0
	v_mov_b32_e32 v119, v0
	v_mov_b32_e32 v72, v0
	v_mov_b32_e32 v73, v0
	v_mov_b32_e32 v74, v0
	v_mov_b32_e32 v75, v0
	v_mov_b32_e32 v76, v0
	v_mov_b32_e32 v77, v0
	v_mov_b32_e32 v78, v0
	v_mov_b32_e32 v79, v0
	v_mov_b32_e32 v88, v0
	v_mov_b32_e32 v89, v0
	v_mov_b32_e32 v90, v0
	v_mov_b32_e32 v91, v0
	v_mov_b32_e32 v92, v0
	v_mov_b32_e32 v93, v0
	v_mov_b32_e32 v94, v0
	v_mov_b32_e32 v95, v0
	v_mov_b32_e32 v104, v0
	v_mov_b32_e32 v105, v0
	v_mov_b32_e32 v106, v0
	v_mov_b32_e32 v107, v0
	v_mov_b32_e32 v108, v0
	v_mov_b32_e32 v109, v0
	v_mov_b32_e32 v110, v0
	v_mov_b32_e32 v111, v0
	v_mov_b32_e32 v120, v0
	v_mov_b32_e32 v121, v0
	v_mov_b32_e32 v122, v0
	v_mov_b32_e32 v123, v0
	v_mov_b32_e32 v124, v0
	v_mov_b32_e32 v125, v0
	v_mov_b32_e32 v126, v0
	v_mov_b32_e32 v127, v0
	s_nop 0
	s_nop 0
	s_nop 0

.Lxb4_done:
	s_waitcnt vmcnt(0)
.LBB0_1118:
	s_or_b64 exec, exec, s[0:1]
	s_waitcnt lgkmcnt(0)
	s_barrier

.LBB0_1130:
	s_cmp_lt_i32 s76, 1
	s_cselect_b64 s[26:27], -1, 0
	s_add_u32 s34, s34, 0x80080
	s_addc_u32 s35, s35, 0
	v_mov_b32_e32 v2, v0
	v_mov_b32_e32 v3, v0
	s_add_u32 s18, s2, 0x100
	v_mov_b32_e32 v1, v0
	v_mov_b32_e32 v84, 0
	v_mov_b64_e32 v[6:7], v[2:3]
	v_mov_b64_e32 v[10:11], v[2:3]
	v_mov_b64_e32 v[22:23], v[2:3]
	v_mov_b64_e32 v[26:27], v[2:3]
	v_mov_b64_e32 v[38:39], v[2:3]
	v_mov_b64_e32 v[42:43], v[2:3]
	v_mov_b64_e32 v[54:55], v[2:3]
	v_mov_b64_e32 v[58:59], v[2:3]
	v_mov_b64_e32 v[14:15], v[2:3]
	v_mov_b64_e32 v[18:19], v[2:3]
	v_mov_b64_e32 v[30:31], v[2:3]
	v_mov_b64_e32 v[34:35], v[2:3]
	v_mov_b64_e32 v[46:47], v[2:3]
	v_mov_b64_e32 v[50:51], v[2:3]
	v_mov_b64_e32 v[62:63], v[2:3]
	v_mov_b64_e32 v[66:67], v[2:3]
	v_mov_b64_e32 v[70:71], v[2:3]
	v_mov_b64_e32 v[74:75], v[2:3]
	v_mov_b64_e32 v[78:79], v[2:3]
	v_mov_b64_e32 v[82:83], v[2:3]
	v_mov_b64_e32 v[94:95], v[2:3]
	v_mov_b64_e32 v[98:99], v[2:3]
	v_mov_b64_e32 v[110:111], v[2:3]
	v_mov_b64_e32 v[114:115], v[2:3]
	s_addc_u32 s41, s3, 0
	s_mov_b32 s77, -2
	v_cndmask_b32_e64 v217, 0, 1, s[26:27]
	v_mov_b64_e32 v[4:5], v[0:1]
	v_mov_b64_e32 v[8:9], v[0:1]
	v_mov_b64_e32 v[20:21], v[0:1]
	v_mov_b64_e32 v[24:25], v[0:1]
	v_mov_b64_e32 v[36:37], v[0:1]
	v_mov_b64_e32 v[40:41], v[0:1]
	v_mov_b64_e32 v[52:53], v[0:1]
	v_mov_b64_e32 v[56:57], v[0:1]
	v_mov_b64_e32 v[12:13], v[0:1]
	v_mov_b64_e32 v[16:17], v[0:1]
	v_mov_b64_e32 v[28:29], v[0:1]
	v_mov_b64_e32 v[32:33], v[0:1]
	v_mov_b64_e32 v[44:45], v[0:1]
	v_mov_b64_e32 v[48:49], v[0:1]
	v_mov_b64_e32 v[60:61], v[0:1]
	v_mov_b64_e32 v[64:65], v[0:1]
	v_mov_b64_e32 v[68:69], v[0:1]
	v_mov_b64_e32 v[72:73], v[0:1]
	v_mov_b64_e32 v[76:77], v[0:1]
	v_mov_b64_e32 v[80:81], v[0:1]
	v_mov_b64_e32 v[92:93], v[0:1]
	v_mov_b64_e32 v[96:97], v[0:1]
	v_mov_b64_e32 v[108:109], v[0:1]
	v_mov_b64_e32 v[112:113], v[0:1]
	v_mov_b32_e32 v85, v84
	v_mov_b32_e32 v86, v84
	v_mov_b32_e32 v87, v84
	v_mov_b32_e32 v88, v84
	v_mov_b32_e32 v89, v84
	v_mov_b32_e32 v90, v84
	v_mov_b32_e32 v91, v84
	v_mov_b32_e32 v100, v84
	v_mov_b32_e32 v101, v84
	v_mov_b32_e32 v102, v84
	v_mov_b32_e32 v103, v84
	v_mov_b32_e32 v104, v84
	v_mov_b32_e32 v105, v84
	v_mov_b32_e32 v106, v84
	v_mov_b32_e32 v107, v84
	v_mov_b32_e32 v116, v84
	v_mov_b32_e32 v117, v84
	v_mov_b32_e32 v118, v84
	v_mov_b32_e32 v119, v84
	v_mov_b32_e32 v120, v84
	v_mov_b32_e32 v121, v84
	v_mov_b32_e32 v122, v84
	v_mov_b32_e32 v123, v84
	v_mov_b32_e32 v124, v84
	v_mov_b32_e32 v125, v84
	v_mov_b32_e32 v126, v84
	v_mov_b32_e32 v127, v84
	v_mov_b32_e32 v128, v84
	v_mov_b32_e32 v129, v84
	v_mov_b32_e32 v130, v84
	v_mov_b32_e32 v131, v84
	s_branch .LBB0_1132
	s_nop 0
	s_nop 0
	s_nop 0
	s_nop 0
	s_nop 0
	s_nop 0
	s_nop 0
	s_nop 0
	s_nop 0
	s_nop 0
	s_nop 0
	s_nop 0
	s_nop 0

.Lxb5_done:
	s_waitcnt vmcnt(0)
.LBB0_1269:
	s_or_b64 exec, exec, s[2:3]
	s_waitcnt lgkmcnt(0)
	s_barrier

.LBB0_1281:
	s_cmp_lt_i32 s79, 1
	s_cselect_b64 s[34:35], -1, 0
	s_add_u32 s38, s38, 0x80080
	s_addc_u32 s39, s39, 0
	v_mov_b32_e32 v2, v0
	v_mov_b32_e32 v3, v0
	s_add_u32 s16, s4, 0x100
	v_mov_b32_e32 v1, v0
	v_mov_b32_e32 v112, 0
	v_mov_b64_e32 v[6:7], v[2:3]
	v_mov_b64_e32 v[10:11], v[2:3]
	v_mov_b64_e32 v[22:23], v[2:3]
	v_mov_b64_e32 v[26:27], v[2:3]
	v_mov_b64_e32 v[38:39], v[2:3]
	v_mov_b64_e32 v[42:43], v[2:3]
	v_mov_b64_e32 v[54:55], v[2:3]
	v_mov_b64_e32 v[58:59], v[2:3]
	v_mov_b64_e32 v[14:15], v[2:3]
	v_mov_b64_e32 v[18:19], v[2:3]
	v_mov_b64_e32 v[30:31], v[2:3]
	v_mov_b64_e32 v[34:35], v[2:3]
	v_mov_b64_e32 v[46:47], v[2:3]
	v_mov_b64_e32 v[50:51], v[2:3]
	v_mov_b64_e32 v[62:63], v[2:3]
	v_mov_b64_e32 v[66:67], v[2:3]
	v_mov_b64_e32 v[90:91], v[2:3]
	v_mov_b64_e32 v[106:107], v[2:3]
	v_mov_b64_e32 v[110:111], v[2:3]
	v_mov_b64_e32 v[118:119], v[2:3]
	v_mov_b64_e32 v[126:127], v[2:3]
	v_mov_b64_e32 v[130:131], v[2:3]
	v_mov_b64_e32 v[142:143], v[2:3]
	v_mov_b64_e32 v[146:147], v[2:3]
	s_addc_u32 s27, s5, 0
	s_mov_b32 s84, -2
	v_cndmask_b32_e64 v251, 0, 1, s[34:35]
	v_mov_b64_e32 v[4:5], v[0:1]
	v_mov_b64_e32 v[8:9], v[0:1]
	v_mov_b64_e32 v[20:21], v[0:1]
	v_mov_b64_e32 v[24:25], v[0:1]
	v_mov_b64_e32 v[36:37], v[0:1]
	v_mov_b64_e32 v[40:41], v[0:1]
	v_mov_b64_e32 v[52:53], v[0:1]
	v_mov_b64_e32 v[56:57], v[0:1]
	v_mov_b64_e32 v[12:13], v[0:1]
	v_mov_b64_e32 v[16:17], v[0:1]
	v_mov_b64_e32 v[28:29], v[0:1]
	v_mov_b64_e32 v[32:33], v[0:1]
	v_mov_b64_e32 v[44:45], v[0:1]
	v_mov_b64_e32 v[48:49], v[0:1]
	v_mov_b64_e32 v[60:61], v[0:1]
	v_mov_b64_e32 v[64:65], v[0:1]
	v_mov_b64_e32 v[88:89], v[0:1]
	v_mov_b64_e32 v[104:105], v[0:1]
	v_mov_b64_e32 v[108:109], v[0:1]
	v_mov_b64_e32 v[116:117], v[0:1]
	v_mov_b64_e32 v[124:125], v[0:1]
	v_mov_b64_e32 v[128:129], v[0:1]
	v_mov_b64_e32 v[140:141], v[0:1]
	v_mov_b64_e32 v[144:145], v[0:1]
	v_mov_b32_e32 v113, v112
	v_mov_b32_e32 v114, v112
	v_mov_b32_e32 v115, v112
	v_mov_b32_e32 v120, v112
	v_mov_b32_e32 v121, v112
	v_mov_b32_e32 v122, v112
	v_mov_b32_e32 v123, v112
	v_mov_b32_e32 v132, v112
	v_mov_b32_e32 v133, v112
	v_mov_b32_e32 v134, v112
	v_mov_b32_e32 v135, v112
	v_mov_b32_e32 v136, v112
	v_mov_b32_e32 v137, v112
	v_mov_b32_e32 v138, v112
	v_mov_b32_e32 v139, v112
	v_mov_b32_e32 v148, v112
	v_mov_b32_e32 v149, v112
	v_mov_b32_e32 v150, v112
	v_mov_b32_e32 v151, v112
	v_mov_b32_e32 v152, v112
	v_mov_b32_e32 v153, v112
	v_mov_b32_e32 v154, v112
	v_mov_b32_e32 v155, v112
	v_mov_b32_e32 v156, v112
	v_mov_b32_e32 v157, v112
	v_mov_b32_e32 v158, v112
	v_mov_b32_e32 v159, v112
	v_mov_b32_e32 v160, v112
	v_mov_b32_e32 v161, v112
	v_mov_b32_e32 v162, v112
	v_mov_b32_e32 v163, v112
	s_branch .LBB0_1283
	s_nop 0
	s_nop 0
	s_nop 0
	s_nop 0
	s_nop 0
	s_nop 0
	s_nop 0
	s_nop 0
	s_nop 0
	s_nop 0

.Lxb6_done:
	s_waitcnt vmcnt(0)
.LBB0_1380:
	s_or_b64 exec, exec, s[2:3]
	s_waitcnt lgkmcnt(0)
	s_barrier

.LBB0_1390:
	s_mul_i32 s9, s6, s9
	s_sub_i32 s9, s13, s9
	s_sext_i32_i16 s9, s9
	s_add_i32 s7, s7, s9
	s_lshl_b32 s20, s7, 8
	s_ashr_i32 s21, s20, 31
	s_lshl_b64 s[20:21], s[20:21], 12
	s_add_u32 s86, s80, s20
	v_readlane_b32 s9, v253, 50
	s_addc_u32 s87, s9, s21
	s_and_b64 s[18:19], s[18:19], exec
	s_cselect_b32 s9, s87, s15
	s_cselect_b32 s13, s86, s14
	s_add_u32 s14, s14, 0x80080
	s_addc_u32 s15, s15, 0
	s_add_u32 s20, s16, 0x100
	v_mov_b32_e32 v84, 0
	s_addc_u32 s21, s17, 0
	s_mov_b32 s22, -2
	v_mov_b32_e32 v85, v84
	v_mov_b32_e32 v86, v84
	v_mov_b32_e32 v87, v84
	v_mov_b32_e32 v56, v84
	v_mov_b32_e32 v57, v84
	v_mov_b32_e32 v58, v84
	v_mov_b32_e32 v59, v84
	v_mov_b32_e32 v128, v84
	v_mov_b32_e32 v129, v84
	v_mov_b32_e32 v130, v84
	v_mov_b32_e32 v131, v84
	v_mov_b32_e32 v80, v84
	v_mov_b32_e32 v81, v84
	v_mov_b32_e32 v82, v84
	v_mov_b32_e32 v83, v84
	v_mov_b32_e32 v132, v84
	v_mov_b32_e32 v133, v84
	v_mov_b32_e32 v134, v84
	v_mov_b32_e32 v135, v84
	v_mov_b32_e32 v60, v84
	v_mov_b32_e32 v61, v84
	v_mov_b32_e32 v62, v84
	v_mov_b32_e32 v63, v84
	v_mov_b32_e32 v124, v84
	v_mov_b32_e32 v125, v84
	v_mov_b32_e32 v126, v84
	v_mov_b32_e32 v127, v84
	v_mov_b32_e32 v52, v84
	v_mov_b32_e32 v53, v84
	v_mov_b32_e32 v54, v84
	v_mov_b32_e32 v55, v84
	v_mov_b32_e32 v88, v84
	v_mov_b32_e32 v89, v84
	v_mov_b32_e32 v90, v84
	v_mov_b32_e32 v91, v84
	v_mov_b32_e32 v16, v84
	v_mov_b32_e32 v17, v84
	v_mov_b32_e32 v18, v84
	v_mov_b32_e32 v19, v84
	v_mov_b32_e32 v120, v84
	v_mov_b32_e32 v121, v84
	v_mov_b32_e32 v122, v84
	v_mov_b32_e32 v123, v84
	v_mov_b32_e32 v48, v84
	v_mov_b32_e32 v49, v84
	v_mov_b32_e32 v50, v84
	v_mov_b32_e32 v51, v84
	v_mov_b32_e32 v92, v84
	v_mov_b32_e32 v93, v84
	v_mov_b32_e32 v94, v84
	v_mov_b32_e32 v95, v84
	v_mov_b32_e32 v20, v84
	v_mov_b32_e32 v21, v84
	v_mov_b32_e32 v22, v84
	v_mov_b32_e32 v23, v84
	v_mov_b32_e32 v0, v84
	v_mov_b32_e32 v1, v84
	v_mov_b32_e32 v2, v84
	v_mov_b32_e32 v3, v84
	v_mov_b32_e32 v64, v84
	v_mov_b32_e32 v65, v84
	v_mov_b32_e32 v66, v84
	v_mov_b32_e32 v67, v84
	v_mov_b32_e32 v8, v84
	v_mov_b32_e32 v9, v84
	v_mov_b32_e32 v10, v84
	v_mov_b32_e32 v11, v84
	v_mov_b32_e32 v72, v84
	v_mov_b32_e32 v73, v84
	v_mov_b32_e32 v74, v84
	v_mov_b32_e32 v75, v84
	v_mov_b32_e32 v4, v84
	v_mov_b32_e32 v5, v84
	v_mov_b32_e32 v6, v84
	v_mov_b32_e32 v7, v84
	v_mov_b32_e32 v68, v84
	v_mov_b32_e32 v69, v84
	v_mov_b32_e32 v70, v84
	v_mov_b32_e32 v71, v84
	v_mov_b32_e32 v12, v84
	v_mov_b32_e32 v13, v84
	v_mov_b32_e32 v14, v84
	v_mov_b32_e32 v15, v84
	v_mov_b32_e32 v76, v84
	v_mov_b32_e32 v77, v84
	v_mov_b32_e32 v78, v84
	v_mov_b32_e32 v79, v84
	v_mov_b32_e32 v32, v84
	v_mov_b32_e32 v33, v84
	v_mov_b32_e32 v34, v84
	v_mov_b32_e32 v35, v84
	v_mov_b32_e32 v104, v84
	v_mov_b32_e32 v105, v84
	v_mov_b32_e32 v106, v84
	v_mov_b32_e32 v107, v84
	v_mov_b32_e32 v40, v84
	v_mov_b32_e32 v41, v84
	v_mov_b32_e32 v42, v84
	v_mov_b32_e32 v43, v84
	v_mov_b32_e32 v112, v84
	v_mov_b32_e32 v113, v84
	v_mov_b32_e32 v114, v84
	v_mov_b32_e32 v115, v84
	v_mov_b32_e32 v136, v84
	v_mov_b32_e32 v137, v84
	v_mov_b32_e32 v138, v84
	v_mov_b32_e32 v139, v84
	v_mov_b32_e32 v36, v84
	v_mov_b32_e32 v37, v84
	v_mov_b32_e32 v38, v84
	v_mov_b32_e32 v39, v84
	v_mov_b32_e32 v108, v84
	v_mov_b32_e32 v109, v84
	v_mov_b32_e32 v110, v84
	v_mov_b32_e32 v111, v84
	v_mov_b32_e32 v44, v84
	v_mov_b32_e32 v45, v84
	v_mov_b32_e32 v46, v84
	v_mov_b32_e32 v47, v84
	v_mov_b32_e32 v116, v84
	v_mov_b32_e32 v117, v84
	v_mov_b32_e32 v118, v84
	v_mov_b32_e32 v119, v84
	v_mov_b32_e32 v140, v84
	v_mov_b32_e32 v141, v84
	v_mov_b32_e32 v142, v84
	v_mov_b32_e32 v143, v84
	s_nop 0
	s_nop 0
	s_nop 0
	s_nop 0
	s_nop 0
	s_nop 0
	s_nop 0
	s_nop 0
	s_nop 0
	s_nop 0

.Lxb7_done:
	s_waitcnt vmcnt(0)
.LBB0_1576:
	s_or_b64 exec, exec, s[2:3]
	s_waitcnt lgkmcnt(0)
	s_barrier

.LBB0_1625:
	s_add_i32 s30, s16, -2
	s_add_u32 s26, s26, 0x160080
	s_addc_u32 s27, s27, 0
	s_add_u32 s31, s34, 0x100
	v_mov_b32_e32 v0, 0
	s_addc_u32 s33, s35, 0
	s_mov_b32 s34, 0
	v_mov_b32_e32 v1, v0
	v_mov_b32_e32 v2, v0
	v_mov_b32_e32 v3, v0
	v_mov_b32_e32 v4, v0
	v_mov_b32_e32 v5, v0
	v_mov_b32_e32 v6, v0
	v_mov_b32_e32 v7, v0
	v_mov_b32_e32 v12, v0
	v_mov_b32_e32 v13, v0
	v_mov_b32_e32 v14, v0
	v_mov_b32_e32 v15, v0
	v_mov_b32_e32 v20, v0
	v_mov_b32_e32 v21, v0
	v_mov_b32_e32 v22, v0
	v_mov_b32_e32 v23, v0
	v_mov_b32_e32 v28, v0
	v_mov_b32_e32 v29, v0
	v_mov_b32_e32 v30, v0
	v_mov_b32_e32 v31, v0
	v_mov_b32_e32 v36, v0
	v_mov_b32_e32 v37, v0
	v_mov_b32_e32 v38, v0
	v_mov_b32_e32 v39, v0
	v_mov_b32_e32 v44, v0
	v_mov_b32_e32 v45, v0
	v_mov_b32_e32 v46, v0
	v_mov_b32_e32 v47, v0
	v_mov_b32_e32 v52, v0
	v_mov_b32_e32 v53, v0
	v_mov_b32_e32 v54, v0
	v_mov_b32_e32 v55, v0
	v_mov_b32_e32 v8, v0
	v_mov_b32_e32 v9, v0
	v_mov_b32_e32 v10, v0
	v_mov_b32_e32 v11, v0
	v_mov_b32_e32 v16, v0
	v_mov_b32_e32 v17, v0
	v_mov_b32_e32 v18, v0
	v_mov_b32_e32 v19, v0
	v_mov_b32_e32 v24, v0
	v_mov_b32_e32 v25, v0
	v_mov_b32_e32 v26, v0
	v_mov_b32_e32 v27, v0
	v_mov_b32_e32 v32, v0
	v_mov_b32_e32 v33, v0
	v_mov_b32_e32 v34, v0
	v_mov_b32_e32 v35, v0
	v_mov_b32_e32 v40, v0
	v_mov_b32_e32 v41, v0
	v_mov_b32_e32 v42, v0
	v_mov_b32_e32 v43, v0
	v_mov_b32_e32 v48, v0
	v_mov_b32_e32 v49, v0
	v_mov_b32_e32 v50, v0
	v_mov_b32_e32 v51, v0
	v_mov_b32_e32 v56, v0
	v_mov_b32_e32 v57, v0
	v_mov_b32_e32 v58, v0
	v_mov_b32_e32 v59, v0
	v_mov_b32_e32 v60, v0
	v_mov_b32_e32 v61, v0
	v_mov_b32_e32 v62, v0
	v_mov_b32_e32 v63, v0
	v_mov_b32_e32 v64, v0
	v_mov_b32_e32 v65, v0
	v_mov_b32_e32 v66, v0
	v_mov_b32_e32 v67, v0
	v_mov_b32_e32 v68, v0
	v_mov_b32_e32 v69, v0
	v_mov_b32_e32 v70, v0
	v_mov_b32_e32 v71, v0
	v_mov_b32_e32 v76, v0
	v_mov_b32_e32 v77, v0
	v_mov_b32_e32 v78, v0
	v_mov_b32_e32 v79, v0
	v_mov_b32_e32 v84, v0
	v_mov_b32_e32 v85, v0
	v_mov_b32_e32 v86, v0
	v_mov_b32_e32 v87, v0
	v_mov_b32_e32 v92, v0
	v_mov_b32_e32 v93, v0
	v_mov_b32_e32 v94, v0
	v_mov_b32_e32 v95, v0
	v_mov_b32_e32 v100, v0
	v_mov_b32_e32 v101, v0
	v_mov_b32_e32 v102, v0
	v_mov_b32_e32 v103, v0
	v_mov_b32_e32 v108, v0
	v_mov_b32_e32 v109, v0
	v_mov_b32_e32 v110, v0
	v_mov_b32_e32 v111, v0
	v_mov_b32_e32 v116, v0
	v_mov_b32_e32 v117, v0
	v_mov_b32_e32 v118, v0
	v_mov_b32_e32 v119, v0
	v_mov_b32_e32 v72, v0
	v_mov_b32_e32 v73, v0
	v_mov_b32_e32 v74, v0
	v_mov_b32_e32 v75, v0
	v_mov_b32_e32 v80, v0
	v_mov_b32_e32 v81, v0
	v_mov_b32_e32 v82, v0
	v_mov_b32_e32 v83, v0
	v_mov_b32_e32 v88, v0
	v_mov_b32_e32 v89, v0
	v_mov_b32_e32 v90, v0
	v_mov_b32_e32 v91, v0
	v_mov_b32_e32 v96, v0
	v_mov_b32_e32 v97, v0
	v_mov_b32_e32 v98, v0
	v_mov_b32_e32 v99, v0
	v_mov_b32_e32 v104, v0
	v_mov_b32_e32 v105, v0
	v_mov_b32_e32 v106, v0
	v_mov_b32_e32 v107, v0
	v_mov_b32_e32 v112, v0
	v_mov_b32_e32 v113, v0
	v_mov_b32_e32 v114, v0
	v_mov_b32_e32 v115, v0
	v_mov_b32_e32 v120, v0
	v_mov_b32_e32 v121, v0
	v_mov_b32_e32 v122, v0
	v_mov_b32_e32 v123, v0
	v_mov_b32_e32 v124, v0
	v_mov_b32_e32 v125, v0
	v_mov_b32_e32 v126, v0
	v_mov_b32_e32 v127, v0
	s_nop 0

.Lxb8_done:
	s_waitcnt vmcnt(0)
.LBB0_1722:
	s_or_b64 exec, exec, s[2:3]
	s_waitcnt lgkmcnt(0)
	s_barrier

.Lxb9_done:
	s_waitcnt vmcnt(0)
.LBB0_1769:
	s_or_b64 exec, exec, s[4:5]
	s_waitcnt lgkmcnt(0)
	s_barrier
	s_mov_b64 s[4:5], -1
	s_and_b64 vcc, exec, s[0:1]
	s_cbranch_vccnz .LBB0_1603
	s_branch .LBB0_1604
